# add nt policy on the scan's read-once q/f/i/g loads
# speedup vs baseline: 1.0407x; 1.0018x over previous
; #define LAS __attribute__((address_space(3)))
; __device__ __forceinline__ unsigned cvtpk(float lo, float hi) { return pg8::cvt_pk_bf16(lo, hi); }
; #define SC_LOFFC(c) SC_LOFF(((c) < 128 ? (c) : 128))
; __device__ __forceinline__ void scan_finish(const f32x4& o, const ScanSt& st, const LAS unsigned char* buf, bf16* HIO, size_t off, float gn, int g) {
;     f32x4 tot = {0.f, 0.f, 0.f, 0.f};
; #pragma unroll
;     for (int w8 = 0; w8 < 8; ++w8) tot += *(const LAS f32x4*)(buf + SC_SSQ + (w8 * 16 + 4 * g) * 4);
; #pragma unroll
;     for (int i = 0; i < 4; ++i) { const float val = o[i] * __builtin_amdgcn_rsqf(tot[i] * (1.0f / 128.0f) + EPS) * gn * st.gv[i]; HIO[off + (size_t)i * DM] = (unsigned short)(cvtpk(val, 0.f) & 0xffffu); }
; }
; __device__ __forceinline__ void scan_mfma_phase(const Params& p, LAS unsigned char* lds) {
;     ...
;             scan_load(rawA, P0, P1, SC_LOFFC(i + 3));
;             if (i >= 2) scan_finish(oprev, st1, buf1, HIO, SC_OFF(i - 1), gn, g);
.LBB0_384:
	s_add_i32 s62, s49, 3
	s_min_u32 s16, s62, 0x80
	s_add_i32 s42, s16, -1
	s_lshl_b64 s[54:55], s[42:43], 15
	v_lshl_add_u64 v[2:3], v[122:123], 0, s[54:55]
	global_load_dwordx4 v[12:15], v[2:3], off nt
	v_lshl_add_u64 v[2:3], v[124:125], 0, s[54:55]
	global_load_dwordx4 v[16:19], v[2:3], off nt
	s_cmp_lg_u32 s49, 0
	s_cselect_b64 s[54:55], -1, 0
	s_cmp_eq_u32 s49, 0
	s_cbranch_scc1 .LBB0_386
	s_waitcnt lgkmcnt(2)
	ds_read_b128 v[56:59], v148 offset:29696
	ds_read_b128 v[60:63], v148 offset:29760
	ds_read_b128 v[64:67], v148 offset:29824
	s_add_i32 s42, s49, -2
	s_lshl_b64 s[56:57], s[42:43], 15
	s_waitcnt lgkmcnt(2)
	v_pk_add_f32 v[2:3], v[58:59], 0 op_sel_hi:[1,0]
	v_pk_add_f32 v[68:69], v[56:57], 0 op_sel_hi:[1,0]
	ds_read_b128 v[56:59], v148 offset:29888
	s_waitcnt lgkmcnt(2)
	v_pk_add_f32 v[2:3], v[2:3], v[62:63]
	v_pk_add_f32 v[68:69], v[68:69], v[60:61]
	ds_read_b128 v[60:63], v148 offset:29952
	s_waitcnt lgkmcnt(2)
	v_pk_add_f32 v[2:3], v[2:3], v[66:67]
	v_pk_add_f32 v[64:65], v[68:69], v[64:65]
	s_waitcnt lgkmcnt(1)
	v_pk_add_f32 v[2:3], v[2:3], v[58:59]
	v_pk_add_f32 v[66:67], v[64:65], v[56:57]
	ds_read_b128 v[56:59], v148 offset:30016
	s_waitcnt lgkmcnt(1)
	v_pk_add_f32 v[2:3], v[2:3], v[62:63]
	ds_read_b128 v[62:65], v148 offset:30080
	v_pk_add_f32 v[60:61], v[66:67], v[60:61]
	ds_read_b128 v[66:69], v148 offset:30144
	s_waitcnt lgkmcnt(2)
	v_pk_add_f32 v[56:57], v[60:61], v[56:57]
	v_pk_add_f32 v[2:3], v[2:3], v[58:59]
	s_waitcnt lgkmcnt(1)
	v_pk_add_f32 v[56:57], v[56:57], v[62:63]
	v_pk_add_f32 v[2:3], v[2:3], v[64:65]
	s_waitcnt lgkmcnt(0)
	v_pk_add_f32 v[56:57], v[56:57], v[66:67]
	v_pk_add_f32 v[2:3], v[2:3], v[68:69]
	v_fmamk_f32 v0, v56, 0x3c000000, v151
	v_rsq_f32_e32 v0, v0
	v_fmamk_f32 v56, v57, 0x3c000000, v151
	v_rsq_f32_e32 v56, v56
	v_lshl_add_u64 v[58:59], v[128:129], 0, s[56:57]
	v_mul_f32_e32 v0, v100, v0
	s_waitcnt vmcnt(4)
	v_mul_f32_e32 v0, v159, v0
	v_mul_f32_e32 v0, v55, v0
	v_cvt_pk_bf16_f32 v0, v0, s0
	v_fmamk_f32 v2, v2, 0x3c000000, v151
	global_store_short v[58:59], v0, off
	v_mul_f32_e32 v0, v101, v56
	v_rsq_f32_e32 v2, v2
	v_mul_f32_e32 v0, v159, v0
	v_mul_f32_e32 v0, v54, v0
	v_cvt_pk_bf16_f32 v0, v0, s0
	global_store_short v[58:59], v0, off offset:2048
	v_mul_f32_e32 v0, v102, v2
	v_mul_f32_e32 v0, v159, v0
	v_fmamk_f32 v3, v3, 0x3c000000, v151
	v_mul_f32_e32 v0, v53, v0
	v_rsq_f32_e32 v53, v3
	v_add_co_u32_e32 v2, vcc, 0x1000, v58
	v_cvt_pk_bf16_f32 v0, v0, s0
	s_nop 0
	v_addc_co_u32_e32 v3, vcc, 0, v59, vcc
	global_store_short v[2:3], v0, off
	v_mul_f32_e32 v0, v103, v53
	v_mul_f32_e32 v0, v159, v0
	v_mul_f32_e32 v0, v52, v0
	v_cvt_pk_bf16_f32 v0, v0, s0
	global_store_short v[2:3], v0, off offset:2048

; #define LAS __attribute__((address_space(3)))
; __device__ __forceinline__ unsigned cvtpk(float lo, float hi) { return pg8::cvt_pk_bf16(lo, hi); }
; #define SC_BAR() asm volatile("s_waitcnt lgkmcnt(0)\n\ts_barrier" ::: "memory")
; #define SC_LOFFC(c) SC_LOFF(((c) < 128 ? (c) : 128))
; __device__ __forceinline__ void scan_finish(const f32x4& o, const ScanSt& st, const LAS unsigned char* buf, bf16* HIO, size_t off, float gn, int g) {
;     f32x4 tot = {0.f, 0.f, 0.f, 0.f};
; #pragma unroll
;     for (int w8 = 0; w8 < 8; ++w8) tot += *(const LAS f32x4*)(buf + SC_SSQ + (w8 * 16 + 4 * g) * 4);
; #pragma unroll
;     for (int i = 0; i < 4; ++i) { const float val = o[i] * __builtin_amdgcn_rsqf(tot[i] * (1.0f / 128.0f) + EPS) * gn * st.gv[i]; HIO[off + (size_t)i * DM] = (unsigned short)(cvtpk(val, 0.f) & 0xffffu); }
; }
; __device__ __forceinline__ void scan_mfma_phase(const Params& p, LAS unsigned char* lds) {
;     ...
;             scan_stage(rawB, SC_SLOT(i + 2), tid_);
;             SC_BAR();
;             scan_load(rawB, P0, P1, SC_LOFFC(i + 4));
;             if (i >= 2) scan_finish(oprev, st0, buf0, HIO, SC_OFF(i), gn, g);
.LBB0_414:
	s_add_i32 s60, s49, 2
	s_mul_i32 s16, s60, 0xab
	s_bfe_u32 s16, s16, 0x70009
	s_mul_i32 s16, s16, 3
	s_sub_i32 s16, s60, s16
	s_and_b32 s16, s16, 0xff
	s_lshl_b32 s16, s16, 14
	s_add_i32 s61, s16, 0
	s_min_u32 s16, s49, 0x7c
	v_add_u32_e32 v0, s61, v113
	s_lshl_b32 s16, s16, 4
	v_add3_u32 v0, v0, v115, v119
	s_add_i32 s42, s16, 48
	s_waitcnt vmcnt(3)
	ds_write_b128 v0, v[4:7] offset:32768
	s_waitcnt vmcnt(2)
	ds_write_b128 v0, v[8:11] offset:40960
	v_lshl_add_u64 v[4:5], v[120:121], 0, s[42:43]
	v_lshlrev_b64 v[8:9], 11, v[4:5]
	v_lshl_or_b32 v8, v158, 1, v8
	s_waitcnt lgkmcnt(0)
	s_barrier
	v_lshl_add_u64 v[4:5], v[106:107], 0, v[8:9]
	v_lshl_add_u64 v[8:9], v[108:109], 0, v[8:9]
	global_load_dwordx4 v[4:7], v[4:5], off nt
	s_andn2_b64 vcc, exec, s[54:55]
	global_load_dwordx4 v[8:11], v[8:9], off nt
	s_cbranch_vccnz .LBB0_416
	s_waitcnt lgkmcnt(4)
	ds_read_b128 v[20:23], v152 offset:13312
	s_waitcnt lgkmcnt(3)
	ds_read_b128 v[24:27], v152 offset:13376
	ds_read_b128 v[28:31], v152 offset:13440
	v_lshlrev_b32_e32 v0, 16, v169
	s_add_i32 s42, s49, -1
	s_waitcnt lgkmcnt(2)
	v_pk_add_f32 v[22:23], v[22:23], 0 op_sel_hi:[1,0]
	v_pk_add_f32 v[32:33], v[20:21], 0 op_sel_hi:[1,0]
	s_waitcnt lgkmcnt(1)
	v_pk_add_f32 v[26:27], v[22:23], v[26:27]
	ds_read_b128 v[20:23], v152 offset:13504
	v_pk_add_f32 v[32:33], v[32:33], v[24:25]
	s_waitcnt lgkmcnt(1)
	v_pk_add_f32 v[30:31], v[26:27], v[30:31]
	ds_read_b128 v[24:27], v152 offset:13568
	v_pk_add_f32 v[28:29], v[32:33], v[28:29]
	s_waitcnt lgkmcnt(1)
	v_pk_add_f32 v[30:31], v[30:31], v[22:23]
	v_pk_add_f32 v[32:33], v[28:29], v[20:21]
	ds_read_b128 v[20:23], v152 offset:13632
	s_waitcnt lgkmcnt(1)
	v_pk_add_f32 v[34:35], v[30:31], v[26:27]
	ds_read_b128 v[26:29], v152 offset:13696
	v_pk_add_f32 v[24:25], v[32:33], v[24:25]
	ds_read_b128 v[30:33], v152 offset:13760
	s_waitcnt lgkmcnt(2)
	v_pk_add_f32 v[20:21], v[24:25], v[20:21]
	v_pk_add_f32 v[22:23], v[34:35], v[22:23]
	s_waitcnt lgkmcnt(1)
	v_pk_add_f32 v[20:21], v[20:21], v[26:27]
	v_pk_add_f32 v[22:23], v[22:23], v[28:29]
	s_waitcnt lgkmcnt(0)
	v_pk_add_f32 v[20:21], v[20:21], v[30:31]
	v_pk_add_f32 v[22:23], v[22:23], v[32:33]
	v_fmamk_f32 v20, v20, 0x3c000000, v151
	v_rsq_f32_e32 v20, v20
	v_fmamk_f32 v21, v21, 0x3c000000, v151
	v_rsq_f32_e32 v21, v21
	s_lshl_b64 s[54:55], s[42:43], 15
	v_mul_f32_e32 v20, v100, v20
	v_mul_f32_e32 v20, v159, v20
	v_mul_f32_e32 v0, v20, v0
	v_lshl_add_u64 v[24:25], v[128:129], 0, s[54:55]
	v_cvt_pk_bf16_f32 v0, v0, s0
	v_fmamk_f32 v20, v22, 0x3c000000, v151
	global_store_short v[24:25], v0, off
	v_mul_f32_e32 v0, v101, v21
	v_rsq_f32_e32 v20, v20
	v_lshlrev_b32_e32 v36, 16, v170
	v_mul_f32_e32 v0, v159, v0
	v_mul_f32_e32 v0, v0, v36
	v_cvt_pk_bf16_f32 v0, v0, s0
	v_fmamk_f32 v21, v23, 0x3c000000, v151
	global_store_short v[24:25], v0, off offset:2048
	v_mul_f32_e32 v0, v102, v20
	v_rsq_f32_e32 v22, v21
	v_lshlrev_b32_e32 v37, 16, v171
	v_mul_f32_e32 v0, v159, v0
	v_mul_f32_e32 v0, v0, v37
	v_add_co_u32_e32 v20, vcc, 0x1000, v24
	v_cvt_pk_bf16_f32 v0, v0, s0
	s_nop 0
	v_addc_co_u32_e32 v21, vcc, 0, v25, vcc
	global_store_short v[20:21], v0, off
	v_mul_f32_e32 v0, v103, v22
	v_lshlrev_b32_e32 v38, 16, v172
	v_mul_f32_e32 v0, v159, v0
	v_mul_f32_e32 v0, v0, v38
	v_cvt_pk_bf16_f32 v0, v0, s0
	global_store_short v[20:21], v0, off offset:2048

; __global__ void __launch_bounds__(NTHREADS, 2) fwd_megakernel(Params p) {
	.amdhsa_kernel _Z14fwd_megakernel6Params
		.amdhsa_group_segment_fixed_size 0
		.amdhsa_private_segment_fixed_size 0
		.amdhsa_kernarg_size 424
		.amdhsa_user_sgpr_count 2
		.amdhsa_user_sgpr_dispatch_ptr 0
		.amdhsa_user_sgpr_queue_ptr 0
		.amdhsa_user_sgpr_kernarg_segment_ptr 1
		.amdhsa_user_sgpr_dispatch_id 0
		.amdhsa_user_sgpr_kernarg_preload_length 0
		.amdhsa_user_sgpr_kernarg_preload_offset 0
		.amdhsa_user_sgpr_private_segment_size 0
		.amdhsa_uses_dynamic_stack 0
		.amdhsa_enable_private_segment 0
		.amdhsa_system_sgpr_workgroup_id_x 1
		.amdhsa_system_sgpr_workgroup_id_y 0
		.amdhsa_system_sgpr_workgroup_id_z 0
		.amdhsa_system_sgpr_workgroup_info 0
		.amdhsa_system_vgpr_workitem_id 2
		.amdhsa_next_free_vgpr 254
		.amdhsa_next_free_sgpr 101
		.amdhsa_accum_offset 256
		.amdhsa_reserve_vcc 1
		.amdhsa_float_round_mode_32 0
		.amdhsa_float_round_mode_16_64 0
		.amdhsa_float_denorm_mode_32 3
		.amdhsa_float_denorm_mode_16_64 3
		.amdhsa_dx10_clamp 1
		.amdhsa_ieee_mode 1
		.amdhsa_fp16_overflow 0
		.amdhsa_tg_split 0
		.amdhsa_exception_fp_ieee_invalid_op 0
		.amdhsa_exception_fp_denorm_src 0
		.amdhsa_exception_fp_ieee_div_zero 0
		.amdhsa_exception_fp_ieee_overflow 0
		.amdhsa_exception_fp_ieee_underflow 0
		.amdhsa_exception_fp_ieee_inexact 0
		.amdhsa_exception_int_div_zero 0
	.end_amdhsa_kernel

; __global__ void __launch_bounds__(NTHREADS, 2) fwd_megakernel(Params p) {
.Lfunc_end0:
	.size	_Z14fwd_megakernel6Params, .Lfunc_end0-_Z14fwd_megakernel6Params
	.set _Z14fwd_megakernel6Params.num_vgpr, 254
	.set _Z14fwd_megakernel6Params.num_agpr, 0
	.set _Z14fwd_megakernel6Params.numbered_sgpr, 101
	.set _Z14fwd_megakernel6Params.num_named_barrier, 0
	.set _Z14fwd_megakernel6Params.private_seg_size, 0
	.set _Z14fwd_megakernel6Params.uses_vcc, 1
	.set _Z14fwd_megakernel6Params.uses_flat_scratch, 0
	.set _Z14fwd_megakernel6Params.has_dyn_sized_stack, 0
	.set _Z14fwd_megakernel6Params.has_recursion, 0
	.set _Z14fwd_megakernel6Params.has_indirect_call, 0

; __global__ void __launch_bounds__(NTHREADS, 2) fwd_megakernel(Params p) {
amdhsa.kernels:
  - .agpr_count:     0
    .args:
      - .offset:         0
        .size:           168
        .value_kind:     by_value
      - .offset:         168
        .size:           4
        .value_kind:     hidden_block_count_x
      - .offset:         172
        .size:           4
        .value_kind:     hidden_block_count_y
      - .offset:         176
        .size:           4
        .value_kind:     hidden_block_count_z
      - .offset:         180
        .size:           2
        .value_kind:     hidden_group_size_x
      - .offset:         182
        .size:           2
        .value_kind:     hidden_group_size_y
      - .offset:         184
        .size:           2
        .value_kind:     hidden_group_size_z
      - .offset:         186
        .size:           2
        .value_kind:     hidden_remainder_x
      - .offset:         188
        .size:           2
        .value_kind:     hidden_remainder_y
      - .offset:         190
        .size:           2
        .value_kind:     hidden_remainder_z
      - .offset:         208
        .size:           8
        .value_kind:     hidden_global_offset_x
      - .offset:         216
        .size:           8
        .value_kind:     hidden_global_offset_y
      - .offset:         224
        .size:           8
        .value_kind:     hidden_global_offset_z
      - .offset:         232
        .size:           2
        .value_kind:     hidden_grid_dims
      - .offset:         256
        .size:           8
        .value_kind:     hidden_multigrid_sync_arg
      - .offset:         288
        .size:           4
        .value_kind:     hidden_dynamic_lds_size
    .group_segment_fixed_size: 0
    .kernarg_segment_align: 8
    .kernarg_segment_size: 424
    .language:       OpenCL C
    .language_version:
      - 2
      - 0
    .max_flat_workgroup_size: 512
    .name:           _Z14fwd_megakernel6Params
    .private_segment_fixed_size: 0
    .sgpr_count:     107
    .sgpr_spill_count: 8
    .symbol:         _Z14fwd_megakernel6Params.kd
    .uniform_work_group_size: 1
    .uses_dynamic_stack: false
    .vgpr_count:     254
    .vgpr_spill_count: 0
    .wavefront_size: 64
